# speedup vs baseline: 1.0004x; 1.0004x over previous
; #define LAS __attribute__((address_space(3)))
; __device__ __forceinline__ void rw_combine8(const int tid, LAS float* lds, const float* PQ, float* SIN, int task) {
;     const int head = task >> 3, r0 = (task & 7) * 8, row = tid >> 6, k = tid & 63;
;     LAS float* Sl0 = lds;
;     LAS float* Pl0 = lds + 1024;
;     float sval = 0.f;
;     f32x4 pp0[4], pp1[4]; float pq[4];
;     const float* Pb = PQ + (size_t)((head * NCH) * 2 + 1) * 4096; const float* Qb = PQ + (size_t)((head * NCH) * 2) * 4096 + (r0 + row) * 64 + k;
; #pragma unroll
;     for (int d = 0; d < 4; ++d) { pp0[d] = *(const f32x4*)(Pb + (size_t)d * 8192 + tid * 4); pp1[d] = *(const f32x4*)(Pb + (size_t)d * 8192 + (tid + NTHR) * 4); pq[d] = Qb[(size_t)d * 8192]; }
;     for (int c0 = 0; c0 < NCH; c0 += 4) {
.LBB0_91:
	s_and_b64 vcc, exec, s[0:1]
	s_cbranch_vccz .LBB0_209
	s_cmp_lt_i32 s44, 64
	s_cbranch_scc0 .LBB0_116
	s_waitcnt lgkmcnt(0)
	s_add_u32 s7, s18, 0x28300000
	s_addc_u32 s8, s19, 0
	s_and_b32 s6, s28, 0xffffffc0
	s_lshl_b32 s0, s6, 1
	s_or_b32 s4, s0, 1
	s_ashr_i32 s5, s4, 31
	s_lshl_b64 s[4:5], s[4:5], 14
	s_add_u32 s4, s7, s4
	s_addc_u32 s5, s8, s5
	s_ashr_i32 s1, s0, 31
	s_lshl_b64 s[0:1], s[0:1], 14
	s_add_u32 s0, s7, s0
	s_addc_u32 s1, s8, s1
	s_lshl_b32 s7, s44, 9
	s_and_b32 s7, s7, 0xe00
	s_waitcnt vmcnt(5)
	v_add_u32_e32 v0, s7, v148
	v_and_b32_e32 v0, 0xffffffc0, v0
	v_ashrrev_i32_e32 v1, 31, v0
	v_lshlrev_b32_e32 v34, 2, v148
	s_waitcnt vmcnt(4)
	v_lshlrev_b64 v[38:39], 2, v[0:1]
	v_add_u32_e32 v36, 0x800, v34
	v_lshl_add_u64 v[0:1], s[0:1], 0, v[38:39]
	s_waitcnt vmcnt(3)
	v_lshlrev_b32_e32 v42, 2, v188
	v_mov_b32_e32 v43, v144
	v_ashrrev_i32_e32 v35, 31, v34
	v_ashrrev_i32_e32 v37, 31, v36
	s_add_u32 s0, s4, 0x18000
	v_lshl_add_u64 v[32:33], v[0:1], 0, v[42:43]
	s_addc_u32 s1, s5, 0
	v_lshlrev_b64 v[0:1], 2, v[36:37]
	v_lshlrev_b64 v[2:3], 2, v[34:35]
	v_lshl_add_u64 v[28:29], s[0:1], 0, v[0:1]
	v_lshl_add_u64 v[24:25], s[0:1], 0, v[2:3]
	s_add_u32 s0, s4, 0x10000
	s_addc_u32 s1, s5, 0
	s_waitcnt vmcnt(0)
	v_lshl_add_u64 v[20:21], s[0:1], 0, v[0:1]
	v_lshl_add_u64 v[16:17], s[0:1], 0, v[2:3]
	s_add_u32 s0, s4, 0x8000
	s_addc_u32 s1, s5, 0
	v_lshl_add_u64 v[12:13], s[0:1], 0, v[0:1]
	v_lshl_add_u64 v[8:9], s[0:1], 0, v[2:3]
	s_mov_b32 s0, 0x8000
	v_add_co_u32_e32 v18, vcc, s0, v32
	s_mov_b32 s0, 0x10000
	s_nop 0
	v_addc_co_u32_e32 v19, vcc, 0, v33, vcc
	v_lshl_add_u64 v[4:5], s[4:5], 0, v[0:1]
	v_lshl_add_u64 v[0:1], s[4:5], 0, v[2:3]
	v_add_co_u32_e32 v26, vcc, s0, v32
	global_load_dwordx4 v[0:3], v[0:1], off
	s_nop 0
	global_load_dwordx4 v[4:7], v[4:5], off
	s_nop 0
	global_load_dword v49, v[32:33], off
	s_nop 0
	global_load_dwordx4 v[8:11], v[8:9], off
	s_nop 0
	global_load_dwordx4 v[12:15], v[12:13], off
	v_addc_co_u32_e32 v27, vcc, 0, v33, vcc
	s_mov_b32 s0, 0x18000
	v_add_co_u32_e32 v40, vcc, s0, v32
	global_load_dword v50, v[18:19], off
	s_nop 0
	global_load_dwordx4 v[16:19], v[16:17], off
	s_nop 0
	global_load_dwordx4 v[20:23], v[20:21], off
	s_nop 0
	global_load_dword v48, v[26:27], off
	s_nop 0
	global_load_dwordx4 v[24:27], v[24:25], off
	s_nop 0
	global_load_dwordx4 v[28:31], v[28:29], off
	v_addc_co_u32_e32 v41, vcc, 0, v33, vcc
	global_load_dword v47, v[40:41], off
	v_lshl_add_u64 v[38:39], s[18:19], 0, v[38:39]
	v_lshl_add_u32 v41, v148, 4, 0
	v_mul_lo_u32 v44, v148, -12
	v_lshl_add_u64 v[38:39], v[38:39], 0, v[42:43]
	s_mov_b64 s[0:1], 0x29300000
	v_and_b32_e32 v43, 0x3fffffc0, v148
	v_add_u32_e32 v40, v41, v44
	v_lshl_add_u64 v[38:39], v[38:39], 0, s[0:1]
	v_lshl_add_u32 v45, v43, 2, 0
	v_add_u32_e32 v46, 0, v42
	v_mad_u64_u32 v[42:43], s[0:1], v148, 12, v[40:41]
	s_mov_b32 s7, 0
	v_mov_b32_e32 v51, 0
	v_and_b32_e32 v134, 3, v188
	v_lshrrev_b32_e32 v133, 2, v188
	v_lshl_add_u32 v133, v134, 2, v133
	v_and_b32_e32 v133, 15, v133
	v_lshlrev_b32_e32 v133, 4, v133
	v_lshl_add_u32 v133, v134, 12, v133
	v_lshrrev_b32_e32 v132, 6, v148
	v_lshlrev_b32_e32 v132, 8, v132
	v_lshl_add_u32 v132, v134, 6, v132
	v_lshrrev_b32_e32 v137, 8, v148
	v_and_b32_e32 v138, 15, v148
	v_lshl_add_u32 v138, v137, 2, v138
	v_lshrrev_b32_e32 v139, 4, v148
	v_lshlrev_b32_e32 v139, 8, v139
	v_and_b32_e32 v140, 15, v138
	v_lshl_add_u32 v135, v140, 4, v139
	v_add_u32_e32 v138, 8, v138
	v_and_b32_e32 v138, 15, v138
	v_lshl_add_u32 v136, v138, 4, v139
	s_branch .LBB0_96

; #define LAS __attribute__((address_space(3)))
; __device__ __forceinline__ void rw_combine8(const int tid, LAS float* lds, const float* PQ, float* SIN, int task) {
;     ...
;     for (int c0 = 0; c0 < NCH; c0 += 4) {
; #pragma unroll
;         for (int d = 0; d < 4; ++d) {
;             const int c = c0 + d;
;             SIN[(size_t)(head * NCH + c) * 4096 + (r0 + row) * 64 + k] = sval;
;             if (c < NCH - 1) {
;                 LAS float* Sl = Sl0 + (d & 1) * 512; LAS float* Pl = Pl0 + (d & 1) * 4096;
;                 *(LAS f32x4*)(Pl + tid * 4) = pp0[d]; *(LAS f32x4*)(Pl + (tid + NTHR) * 4) = pp1[d]; Sl[row * 64 + k] = sval;
;                 float acc = pq[d];
;                 if (c + 4 < NCH - 1) { pp0[d] = *(const f32x4*)(Pb + (size_t)(c + 4) * 8192 + tid * 4); pp1[d] = *(const f32x4*)(Pb + (size_t)(c + 4) * 8192 + (tid + NTHR) * 4); pq[d] = Qb[(size_t)(c + 4) * 8192]; }
.LBB0_96:
	s_or_b32 s0, s7, s6
	s_ashr_i32 s1, s0, 31
	s_lshl_b64 s[0:1], s[0:1], 14
	v_lshl_add_u64 v[52:53], v[38:39], 0, s[0:1]
	s_cmp_gt_u32 s7, 58
	global_store_dword v[52:53], v51, off
	s_waitcnt vmcnt(12)
	ds_write_b128 v135, v[0:3] offset:4096
	s_waitcnt vmcnt(11)
	ds_write_b128 v136, v[4:7] offset:12288
	ds_write_b32 v40, v51
	s_cbranch_scc1 .LBB0_98
	s_lshl_b32 s0, s7, 13
	s_add_i32 s12, s0, 0x8000
	s_lshl_b64 s[0:1], s[12:13], 2
	s_add_u32 s8, s4, s0
	s_addc_u32 s9, s5, s1
	v_lshl_add_u64 v[0:1], v[34:35], 2, s[8:9]
	v_lshl_add_u64 v[4:5], v[36:37], 2, s[8:9]
	v_lshl_add_u64 v[52:53], v[32:33], 0, s[0:1]
	global_load_dwordx4 v[0:3], v[0:1], off
	s_nop 0
	global_load_dwordx4 v[4:7], v[4:5], off
	s_nop 0
	global_load_dword v43, v[52:53], off
	s_branch .LBB0_99

; #define LAS __attribute__((address_space(3)))
; __device__ __forceinline__ void rw_combine8(const int tid, LAS float* lds, const float* PQ, float* SIN, int task) {
;     ...
;         for (int d = 0; d < 4; ++d) {
;             const int c = c0 + d;
;             SIN[(size_t)(head * NCH + c) * 4096 + (r0 + row) * 64 + k] = sval;
;             if (c < NCH - 1) {
;                 LAS float* Sl = Sl0 + (d & 1) * 512; LAS float* Pl = Pl0 + (d & 1) * 4096;
;                 *(LAS f32x4*)(Pl + tid * 4) = pp0[d]; *(LAS f32x4*)(Pl + (tid + NTHR) * 4) = pp1[d]; Sl[row * 64 + k] = sval;
;                 float acc = pq[d];
;                 if (c + 4 < NCH - 1) { pp0[d] = *(const f32x4*)(Pb + (size_t)(c + 4) * 8192 + tid * 4); pp1[d] = *(const f32x4*)(Pb + (size_t)(c + 4) * 8192 + (tid + NTHR) * 4); pq[d] = Qb[(size_t)(c + 4) * 8192]; }
;                 __syncthreads();
; #pragma unroll 1
;                 for (int j8 = 0; j8 < 2; ++j8) {
; #pragma unroll
;                     for (int jj = 0; jj < 8; ++jj) { const int j4 = j8 * 8 + jj; const f32x4 s4 = *(const LAS f32x4*)(Sl + row * 64 + j4 * 4);
;                         acc += s4.x * Pl[(j4 * 4) * 64 + k] + s4.y * Pl[(j4 * 4 + 1) * 64 + k] + s4.z * Pl[(j4 * 4 + 2) * 64 + k] + s4.w * Pl[(j4 * 4 + 3) * 64 + k]; } }
;                 sval = acc;
.LBB0_99:
	s_mov_b32 s8, 0
	s_mov_b64 s[0:1], -1
	s_waitcnt lgkmcnt(0)
	s_barrier
	ds_read_b128 v[52:55], v132 offset:0
	ds_read_b128 v[56:59], v132 offset:16
	ds_read_b128 v[60:63], v132 offset:32
	ds_read_b128 v[64:67], v132 offset:48
	ds_read_b128 v[68:71], v133 offset:4096
	ds_read_b128 v[72:75], v133 offset:4352
	ds_read_b128 v[76:79], v133 offset:4608
	ds_read_b128 v[80:83], v133 offset:4864
	ds_read_b128 v[84:87], v133 offset:5120
	ds_read_b128 v[88:91], v133 offset:5376
	ds_read_b128 v[92:95], v133 offset:5632
	ds_read_b128 v[96:99], v133 offset:5888
	ds_read_b128 v[100:103], v133 offset:6144
	ds_read_b128 v[104:107], v133 offset:6400
	ds_read_b128 v[108:111], v133 offset:6656
	ds_read_b128 v[112:115], v133 offset:6912
	ds_read_b128 v[116:119], v133 offset:7168
	ds_read_b128 v[120:123], v133 offset:7424
	ds_read_b128 v[124:127], v133 offset:7680
	ds_read_b128 v[128:131], v133 offset:7936
	s_waitcnt lgkmcnt(15)
	v_mul_f32_e32 v137, v52, v68
	v_mul_f32_e32 v138, v52, v69
	v_mul_f32_e32 v139, v52, v70
	v_mul_f32_e32 v140, v52, v71
	s_waitcnt lgkmcnt(14)
	v_fmac_f32_e32 v137, v53, v72
	v_fmac_f32_e32 v138, v53, v73
	v_fmac_f32_e32 v139, v53, v74
	v_fmac_f32_e32 v140, v53, v75
	s_waitcnt lgkmcnt(13)
	v_fmac_f32_e32 v137, v54, v76
	v_fmac_f32_e32 v138, v54, v77
	v_fmac_f32_e32 v139, v54, v78
	v_fmac_f32_e32 v140, v54, v79
	s_waitcnt lgkmcnt(12)
	v_fmac_f32_e32 v137, v55, v80
	v_fmac_f32_e32 v138, v55, v81
	v_fmac_f32_e32 v139, v55, v82
	v_fmac_f32_e32 v140, v55, v83
	s_waitcnt lgkmcnt(11)
	v_fmac_f32_e32 v137, v56, v84
	v_fmac_f32_e32 v138, v56, v85
	v_fmac_f32_e32 v139, v56, v86
	v_fmac_f32_e32 v140, v56, v87
	s_waitcnt lgkmcnt(10)
	v_fmac_f32_e32 v137, v57, v88
	v_fmac_f32_e32 v138, v57, v89
	v_fmac_f32_e32 v139, v57, v90
	v_fmac_f32_e32 v140, v57, v91
	s_waitcnt lgkmcnt(9)
	v_fmac_f32_e32 v137, v58, v92
	v_fmac_f32_e32 v138, v58, v93
	v_fmac_f32_e32 v139, v58, v94
	v_fmac_f32_e32 v140, v58, v95
	s_waitcnt lgkmcnt(8)
	v_fmac_f32_e32 v137, v59, v96
	v_fmac_f32_e32 v138, v59, v97
	v_fmac_f32_e32 v139, v59, v98
	v_fmac_f32_e32 v140, v59, v99
	s_waitcnt lgkmcnt(7)
	v_fmac_f32_e32 v137, v60, v100
	v_fmac_f32_e32 v138, v60, v101
	v_fmac_f32_e32 v139, v60, v102
	v_fmac_f32_e32 v140, v60, v103
	s_waitcnt lgkmcnt(6)
	v_fmac_f32_e32 v137, v61, v104
	v_fmac_f32_e32 v138, v61, v105
	v_fmac_f32_e32 v139, v61, v106
	v_fmac_f32_e32 v140, v61, v107
	s_waitcnt lgkmcnt(5)
	v_fmac_f32_e32 v137, v62, v108
	v_fmac_f32_e32 v138, v62, v109
	v_fmac_f32_e32 v139, v62, v110
	v_fmac_f32_e32 v140, v62, v111
	s_waitcnt lgkmcnt(4)
	v_fmac_f32_e32 v137, v63, v112
	v_fmac_f32_e32 v138, v63, v113
	v_fmac_f32_e32 v139, v63, v114
	v_fmac_f32_e32 v140, v63, v115
	s_waitcnt lgkmcnt(3)
	v_fmac_f32_e32 v137, v64, v116
	v_fmac_f32_e32 v138, v64, v117
	v_fmac_f32_e32 v139, v64, v118
	v_fmac_f32_e32 v140, v64, v119
	s_waitcnt lgkmcnt(2)
	v_fmac_f32_e32 v137, v65, v120
	v_fmac_f32_e32 v138, v65, v121
	v_fmac_f32_e32 v139, v65, v122
	v_fmac_f32_e32 v140, v65, v123
	s_waitcnt lgkmcnt(1)
	v_fmac_f32_e32 v137, v66, v124
	v_fmac_f32_e32 v138, v66, v125
	v_fmac_f32_e32 v139, v66, v126
	v_fmac_f32_e32 v140, v66, v127
	s_waitcnt lgkmcnt(0)
	v_fmac_f32_e32 v137, v67, v128
	v_fmac_f32_e32 v138, v67, v129
	v_fmac_f32_e32 v139, v67, v130
	v_fmac_f32_e32 v140, v67, v131
	v_cmp_eq_u32_e64 s[0:1], 1, v134
	v_add_f32_dpp v137, v137, v137 quad_perm:[1,0,3,2] row_mask:0xf bank_mask:0xf
	v_add_f32_dpp v138, v138, v138 quad_perm:[1,0,3,2] row_mask:0xf bank_mask:0xf
	v_add_f32_dpp v139, v139, v139 quad_perm:[1,0,3,2] row_mask:0xf bank_mask:0xf
	v_add_f32_dpp v140, v140, v140 quad_perm:[1,0,3,2] row_mask:0xf bank_mask:0xf
	v_cmp_eq_u32_e64 s[8:9], 2, v134
	v_add_f32_dpp v137, v137, v137 quad_perm:[2,3,0,1] row_mask:0xf bank_mask:0xf
	v_add_f32_dpp v138, v138, v138 quad_perm:[2,3,0,1] row_mask:0xf bank_mask:0xf
	v_add_f32_dpp v139, v139, v139 quad_perm:[2,3,0,1] row_mask:0xf bank_mask:0xf
	v_add_f32_dpp v140, v140, v140 quad_perm:[2,3,0,1] row_mask:0xf bank_mask:0xf
	v_cmp_eq_u32_e32 vcc, 3, v134
	s_nop 1
	v_cndmask_b32_e64 v137, v137, v138, s[0:1]
	v_cndmask_b32_e64 v137, v137, v139, s[8:9]
	v_cndmask_b32_e32 v137, v137, v140, vcc
	s_waitcnt vmcnt(13)
	v_add_f32_e32 v49, v49, v137
	s_or_b32 s0, s7, 1
	s_or_b32 s8, s0, s6
	s_ashr_i32 s9, s8, 31
	s_lshl_b64 s[8:9], s[8:9], 14
	v_lshl_add_u64 v[52:53], v[38:39], 0, s[8:9]
	v_add_u32_e32 v51, v42, v44
	global_store_dword v[52:53], v49, off
	s_waitcnt vmcnt(10)
	ds_write_b128 v135, v[8:11] offset:20480
	s_waitcnt vmcnt(9)
	ds_write_b128 v136, v[12:15] offset:28672
	ds_write_b32 v51, v49 offset:2048
	s_cmp_gt_u32 s0, 58
	s_waitcnt vmcnt(8)
	v_mov_b32_e32 v49, v50
	s_cbranch_scc1 .LBB0_103
	s_lshl_b32 s0, s0, 13
	s_add_i32 s12, s0, 0x8000
	s_lshl_b64 s[0:1], s[12:13], 2
	s_add_u32 s8, s4, s0
	s_addc_u32 s9, s5, s1
	v_lshl_add_u64 v[8:9], v[34:35], 2, s[8:9]
	v_lshl_add_u64 v[12:13], v[36:37], 2, s[8:9]
	v_lshl_add_u64 v[52:53], v[32:33], 0, s[0:1]
	global_load_dwordx4 v[8:11], v[8:9], off
	s_nop 0
	global_load_dwordx4 v[12:15], v[12:13], off
	s_nop 0
	global_load_dword v49, v[52:53], off
; #define LAS __attribute__((address_space(3)))
; __device__ __forceinline__ void rw_combine8(const int tid, LAS float* lds, const float* PQ, float* SIN, int task) {
;     ...
;         for (int d = 0; d < 4; ++d) {
;             const int c = c0 + d;
;             SIN[(size_t)(head * NCH + c) * 4096 + (r0 + row) * 64 + k] = sval;
;             if (c < NCH - 1) {
;                 LAS float* Sl = Sl0 + (d & 1) * 512; LAS float* Pl = Pl0 + (d & 1) * 4096;
;                 *(LAS f32x4*)(Pl + tid * 4) = pp0[d]; *(LAS f32x4*)(Pl + (tid + NTHR) * 4) = pp1[d]; Sl[row * 64 + k] = sval;
;                 float acc = pq[d];
;                 if (c + 4 < NCH - 1) { pp0[d] = *(const f32x4*)(Pb + (size_t)(c + 4) * 8192 + tid * 4); pp1[d] = *(const f32x4*)(Pb + (size_t)(c + 4) * 8192 + (tid + NTHR) * 4); pq[d] = Qb[(size_t)(c + 4) * 8192]; }
;                 __syncthreads();
; #pragma unroll 1
;                 for (int j8 = 0; j8 < 2; ++j8) {
; #pragma unroll
;                     for (int jj = 0; jj < 8; ++jj) { const int j4 = j8 * 8 + jj; const f32x4 s4 = *(const LAS f32x4*)(Sl + row * 64 + j4 * 4);
;                         acc += s4.x * Pl[(j4 * 4) * 64 + k] + s4.y * Pl[(j4 * 4 + 1) * 64 + k] + s4.z * Pl[(j4 * 4 + 2) * 64 + k] + s4.w * Pl[(j4 * 4 + 3) * 64 + k]; } }
;                 sval = acc;
.LBB0_103:
	s_mov_b32 s8, 0
	s_mov_b64 s[0:1], -1
	s_waitcnt lgkmcnt(0)
	s_barrier
	ds_read_b128 v[52:55], v132 offset:2048
	ds_read_b128 v[56:59], v132 offset:2064
	ds_read_b128 v[60:63], v132 offset:2080
	ds_read_b128 v[64:67], v132 offset:2096
	ds_read_b128 v[68:71], v133 offset:20480
	ds_read_b128 v[72:75], v133 offset:20736
	ds_read_b128 v[76:79], v133 offset:20992
	ds_read_b128 v[80:83], v133 offset:21248
	ds_read_b128 v[84:87], v133 offset:21504
	ds_read_b128 v[88:91], v133 offset:21760
	ds_read_b128 v[92:95], v133 offset:22016
	ds_read_b128 v[96:99], v133 offset:22272
	ds_read_b128 v[100:103], v133 offset:22528
	ds_read_b128 v[104:107], v133 offset:22784
	ds_read_b128 v[108:111], v133 offset:23040
	ds_read_b128 v[112:115], v133 offset:23296
	ds_read_b128 v[116:119], v133 offset:23552
	ds_read_b128 v[120:123], v133 offset:23808
	ds_read_b128 v[124:127], v133 offset:24064
	ds_read_b128 v[128:131], v133 offset:24320
	s_waitcnt lgkmcnt(15)
	v_mul_f32_e32 v137, v52, v68
	v_mul_f32_e32 v138, v52, v69
	v_mul_f32_e32 v139, v52, v70
	v_mul_f32_e32 v140, v52, v71
	s_waitcnt lgkmcnt(14)
	v_fmac_f32_e32 v137, v53, v72
	v_fmac_f32_e32 v138, v53, v73
	v_fmac_f32_e32 v139, v53, v74
	v_fmac_f32_e32 v140, v53, v75
	s_waitcnt lgkmcnt(13)
	v_fmac_f32_e32 v137, v54, v76
	v_fmac_f32_e32 v138, v54, v77
	v_fmac_f32_e32 v139, v54, v78
	v_fmac_f32_e32 v140, v54, v79
	s_waitcnt lgkmcnt(12)
	v_fmac_f32_e32 v137, v55, v80
	v_fmac_f32_e32 v138, v55, v81
	v_fmac_f32_e32 v139, v55, v82
	v_fmac_f32_e32 v140, v55, v83
	s_waitcnt lgkmcnt(11)
	v_fmac_f32_e32 v137, v56, v84
	v_fmac_f32_e32 v138, v56, v85
	v_fmac_f32_e32 v139, v56, v86
	v_fmac_f32_e32 v140, v56, v87
	s_waitcnt lgkmcnt(10)
	v_fmac_f32_e32 v137, v57, v88
	v_fmac_f32_e32 v138, v57, v89
	v_fmac_f32_e32 v139, v57, v90
	v_fmac_f32_e32 v140, v57, v91
	s_waitcnt lgkmcnt(9)
	v_fmac_f32_e32 v137, v58, v92
	v_fmac_f32_e32 v138, v58, v93
	v_fmac_f32_e32 v139, v58, v94
	v_fmac_f32_e32 v140, v58, v95
	s_waitcnt lgkmcnt(8)
	v_fmac_f32_e32 v137, v59, v96
	v_fmac_f32_e32 v138, v59, v97
	v_fmac_f32_e32 v139, v59, v98
	v_fmac_f32_e32 v140, v59, v99
	s_waitcnt lgkmcnt(7)
	v_fmac_f32_e32 v137, v60, v100
	v_fmac_f32_e32 v138, v60, v101
	v_fmac_f32_e32 v139, v60, v102
	v_fmac_f32_e32 v140, v60, v103
	s_waitcnt lgkmcnt(6)
	v_fmac_f32_e32 v137, v61, v104
	v_fmac_f32_e32 v138, v61, v105
	v_fmac_f32_e32 v139, v61, v106
	v_fmac_f32_e32 v140, v61, v107
	s_waitcnt lgkmcnt(5)
	v_fmac_f32_e32 v137, v62, v108
	v_fmac_f32_e32 v138, v62, v109
	v_fmac_f32_e32 v139, v62, v110
	v_fmac_f32_e32 v140, v62, v111
	s_waitcnt lgkmcnt(4)
	v_fmac_f32_e32 v137, v63, v112
	v_fmac_f32_e32 v138, v63, v113
	v_fmac_f32_e32 v139, v63, v114
	v_fmac_f32_e32 v140, v63, v115
	s_waitcnt lgkmcnt(3)
	v_fmac_f32_e32 v137, v64, v116
	v_fmac_f32_e32 v138, v64, v117
	v_fmac_f32_e32 v139, v64, v118
	v_fmac_f32_e32 v140, v64, v119
	s_waitcnt lgkmcnt(2)
	v_fmac_f32_e32 v137, v65, v120
	v_fmac_f32_e32 v138, v65, v121
	v_fmac_f32_e32 v139, v65, v122
	v_fmac_f32_e32 v140, v65, v123
	s_waitcnt lgkmcnt(1)
	v_fmac_f32_e32 v137, v66, v124
	v_fmac_f32_e32 v138, v66, v125
	v_fmac_f32_e32 v139, v66, v126
	v_fmac_f32_e32 v140, v66, v127
	s_waitcnt lgkmcnt(0)
	v_fmac_f32_e32 v137, v67, v128
	v_fmac_f32_e32 v138, v67, v129
	v_fmac_f32_e32 v139, v67, v130
	v_fmac_f32_e32 v140, v67, v131
	v_cmp_eq_u32_e64 s[0:1], 1, v134
	v_add_f32_dpp v137, v137, v137 quad_perm:[1,0,3,2] row_mask:0xf bank_mask:0xf
	v_add_f32_dpp v138, v138, v138 quad_perm:[1,0,3,2] row_mask:0xf bank_mask:0xf
	v_add_f32_dpp v139, v139, v139 quad_perm:[1,0,3,2] row_mask:0xf bank_mask:0xf
	v_add_f32_dpp v140, v140, v140 quad_perm:[1,0,3,2] row_mask:0xf bank_mask:0xf
	v_cmp_eq_u32_e64 s[8:9], 2, v134
	v_add_f32_dpp v137, v137, v137 quad_perm:[2,3,0,1] row_mask:0xf bank_mask:0xf
	v_add_f32_dpp v138, v138, v138 quad_perm:[2,3,0,1] row_mask:0xf bank_mask:0xf
	v_add_f32_dpp v139, v139, v139 quad_perm:[2,3,0,1] row_mask:0xf bank_mask:0xf
	v_add_f32_dpp v140, v140, v140 quad_perm:[2,3,0,1] row_mask:0xf bank_mask:0xf
	v_cmp_eq_u32_e32 vcc, 3, v134
	s_nop 1
	v_cndmask_b32_e64 v137, v137, v138, s[0:1]
	v_cndmask_b32_e64 v137, v137, v139, s[8:9]
	v_cndmask_b32_e32 v137, v137, v140, vcc
	v_add_f32_e32 v50, v50, v137
	s_or_b32 s0, s7, 2
	s_or_b32 s8, s0, s6
	s_ashr_i32 s9, s8, 31
	s_lshl_b64 s[8:9], s[8:9], 14
	v_lshl_add_u64 v[52:53], v[38:39], 0, s[8:9]
	global_store_dword v[52:53], v50, off
	s_waitcnt vmcnt(8)
	ds_write_b128 v135, v[16:19] offset:4096
	s_waitcnt vmcnt(7)
	ds_write_b128 v136, v[20:23] offset:12288
	ds_write_b32 v40, v50
	s_cmp_gt_u32 s0, 58
	s_waitcnt vmcnt(6)
	v_mov_b32_e32 v50, v48
	s_cbranch_scc1 .LBB0_107
	s_lshl_b32 s0, s0, 13
	s_add_i32 s12, s0, 0x8000
	s_lshl_b64 s[0:1], s[12:13], 2
	s_add_u32 s8, s4, s0
	s_addc_u32 s9, s5, s1
	v_lshl_add_u64 v[16:17], v[34:35], 2, s[8:9]
	v_lshl_add_u64 v[20:21], v[36:37], 2, s[8:9]
	v_lshl_add_u64 v[52:53], v[32:33], 0, s[0:1]
	global_load_dwordx4 v[16:19], v[16:17], off
	s_nop 0
	global_load_dwordx4 v[20:23], v[20:21], off
	s_nop 0
	global_load_dword v50, v[52:53], off
; #define LAS __attribute__((address_space(3)))
; __device__ __forceinline__ void rw_combine8(const int tid, LAS float* lds, const float* PQ, float* SIN, int task) {
;     ...
;         for (int d = 0; d < 4; ++d) {
;             const int c = c0 + d;
;             SIN[(size_t)(head * NCH + c) * 4096 + (r0 + row) * 64 + k] = sval;
;             if (c < NCH - 1) {
;                 LAS float* Sl = Sl0 + (d & 1) * 512; LAS float* Pl = Pl0 + (d & 1) * 4096;
;                 *(LAS f32x4*)(Pl + tid * 4) = pp0[d]; *(LAS f32x4*)(Pl + (tid + NTHR) * 4) = pp1[d]; Sl[row * 64 + k] = sval;
;                 float acc = pq[d];
;                 if (c + 4 < NCH - 1) { pp0[d] = *(const f32x4*)(Pb + (size_t)(c + 4) * 8192 + tid * 4); pp1[d] = *(const f32x4*)(Pb + (size_t)(c + 4) * 8192 + (tid + NTHR) * 4); pq[d] = Qb[(size_t)(c + 4) * 8192]; }
;                 __syncthreads();
; #pragma unroll 1
;                 for (int j8 = 0; j8 < 2; ++j8) {
; #pragma unroll
;                     for (int jj = 0; jj < 8; ++jj) { const int j4 = j8 * 8 + jj; const f32x4 s4 = *(const LAS f32x4*)(Sl + row * 64 + j4 * 4);
;                         acc += s4.x * Pl[(j4 * 4) * 64 + k] + s4.y * Pl[(j4 * 4 + 1) * 64 + k] + s4.z * Pl[(j4 * 4 + 2) * 64 + k] + s4.w * Pl[(j4 * 4 + 3) * 64 + k]; } }
;                 sval = acc;
.LBB0_107:
	s_mov_b32 s8, 0
	s_mov_b64 s[0:1], -1
	s_waitcnt lgkmcnt(0)
	s_barrier
	ds_read_b128 v[52:55], v132 offset:0
	ds_read_b128 v[56:59], v132 offset:16
	ds_read_b128 v[60:63], v132 offset:32
	ds_read_b128 v[64:67], v132 offset:48
	ds_read_b128 v[68:71], v133 offset:4096
	ds_read_b128 v[72:75], v133 offset:4352
	ds_read_b128 v[76:79], v133 offset:4608
	ds_read_b128 v[80:83], v133 offset:4864
	ds_read_b128 v[84:87], v133 offset:5120
	ds_read_b128 v[88:91], v133 offset:5376
	ds_read_b128 v[92:95], v133 offset:5632
	ds_read_b128 v[96:99], v133 offset:5888
	ds_read_b128 v[100:103], v133 offset:6144
	ds_read_b128 v[104:107], v133 offset:6400
	ds_read_b128 v[108:111], v133 offset:6656
	ds_read_b128 v[112:115], v133 offset:6912
	ds_read_b128 v[116:119], v133 offset:7168
	ds_read_b128 v[120:123], v133 offset:7424
	ds_read_b128 v[124:127], v133 offset:7680
	ds_read_b128 v[128:131], v133 offset:7936
	s_waitcnt lgkmcnt(15)
	v_mul_f32_e32 v137, v52, v68
	v_mul_f32_e32 v138, v52, v69
	v_mul_f32_e32 v139, v52, v70
	v_mul_f32_e32 v140, v52, v71
	s_waitcnt lgkmcnt(14)
	v_fmac_f32_e32 v137, v53, v72
	v_fmac_f32_e32 v138, v53, v73
	v_fmac_f32_e32 v139, v53, v74
	v_fmac_f32_e32 v140, v53, v75
	s_waitcnt lgkmcnt(13)
	v_fmac_f32_e32 v137, v54, v76
	v_fmac_f32_e32 v138, v54, v77
	v_fmac_f32_e32 v139, v54, v78
	v_fmac_f32_e32 v140, v54, v79
	s_waitcnt lgkmcnt(12)
	v_fmac_f32_e32 v137, v55, v80
	v_fmac_f32_e32 v138, v55, v81
	v_fmac_f32_e32 v139, v55, v82
	v_fmac_f32_e32 v140, v55, v83
	s_waitcnt lgkmcnt(11)
	v_fmac_f32_e32 v137, v56, v84
	v_fmac_f32_e32 v138, v56, v85
	v_fmac_f32_e32 v139, v56, v86
	v_fmac_f32_e32 v140, v56, v87
	s_waitcnt lgkmcnt(10)
	v_fmac_f32_e32 v137, v57, v88
	v_fmac_f32_e32 v138, v57, v89
	v_fmac_f32_e32 v139, v57, v90
	v_fmac_f32_e32 v140, v57, v91
	s_waitcnt lgkmcnt(9)
	v_fmac_f32_e32 v137, v58, v92
	v_fmac_f32_e32 v138, v58, v93
	v_fmac_f32_e32 v139, v58, v94
	v_fmac_f32_e32 v140, v58, v95
	s_waitcnt lgkmcnt(8)
	v_fmac_f32_e32 v137, v59, v96
	v_fmac_f32_e32 v138, v59, v97
	v_fmac_f32_e32 v139, v59, v98
	v_fmac_f32_e32 v140, v59, v99
	s_waitcnt lgkmcnt(7)
	v_fmac_f32_e32 v137, v60, v100
	v_fmac_f32_e32 v138, v60, v101
	v_fmac_f32_e32 v139, v60, v102
	v_fmac_f32_e32 v140, v60, v103
	s_waitcnt lgkmcnt(6)
	v_fmac_f32_e32 v137, v61, v104
	v_fmac_f32_e32 v138, v61, v105
	v_fmac_f32_e32 v139, v61, v106
	v_fmac_f32_e32 v140, v61, v107
	s_waitcnt lgkmcnt(5)
	v_fmac_f32_e32 v137, v62, v108
	v_fmac_f32_e32 v138, v62, v109
	v_fmac_f32_e32 v139, v62, v110
	v_fmac_f32_e32 v140, v62, v111
	s_waitcnt lgkmcnt(4)
	v_fmac_f32_e32 v137, v63, v112
	v_fmac_f32_e32 v138, v63, v113
	v_fmac_f32_e32 v139, v63, v114
	v_fmac_f32_e32 v140, v63, v115
	s_waitcnt lgkmcnt(3)
	v_fmac_f32_e32 v137, v64, v116
	v_fmac_f32_e32 v138, v64, v117
	v_fmac_f32_e32 v139, v64, v118
	v_fmac_f32_e32 v140, v64, v119
	s_waitcnt lgkmcnt(2)
	v_fmac_f32_e32 v137, v65, v120
	v_fmac_f32_e32 v138, v65, v121
	v_fmac_f32_e32 v139, v65, v122
	v_fmac_f32_e32 v140, v65, v123
	s_waitcnt lgkmcnt(1)
	v_fmac_f32_e32 v137, v66, v124
	v_fmac_f32_e32 v138, v66, v125
	v_fmac_f32_e32 v139, v66, v126
	v_fmac_f32_e32 v140, v66, v127
	s_waitcnt lgkmcnt(0)
	v_fmac_f32_e32 v137, v67, v128
	v_fmac_f32_e32 v138, v67, v129
	v_fmac_f32_e32 v139, v67, v130
	v_fmac_f32_e32 v140, v67, v131
	v_cmp_eq_u32_e64 s[0:1], 1, v134
	v_add_f32_dpp v137, v137, v137 quad_perm:[1,0,3,2] row_mask:0xf bank_mask:0xf
	v_add_f32_dpp v138, v138, v138 quad_perm:[1,0,3,2] row_mask:0xf bank_mask:0xf
	v_add_f32_dpp v139, v139, v139 quad_perm:[1,0,3,2] row_mask:0xf bank_mask:0xf
	v_add_f32_dpp v140, v140, v140 quad_perm:[1,0,3,2] row_mask:0xf bank_mask:0xf
	v_cmp_eq_u32_e64 s[8:9], 2, v134
	v_add_f32_dpp v137, v137, v137 quad_perm:[2,3,0,1] row_mask:0xf bank_mask:0xf
	v_add_f32_dpp v138, v138, v138 quad_perm:[2,3,0,1] row_mask:0xf bank_mask:0xf
	v_add_f32_dpp v139, v139, v139 quad_perm:[2,3,0,1] row_mask:0xf bank_mask:0xf
	v_add_f32_dpp v140, v140, v140 quad_perm:[2,3,0,1] row_mask:0xf bank_mask:0xf
	v_cmp_eq_u32_e32 vcc, 3, v134
	s_nop 1
	v_cndmask_b32_e64 v137, v137, v138, s[0:1]
	v_cndmask_b32_e64 v137, v137, v139, s[8:9]
	v_cndmask_b32_e32 v137, v137, v140, vcc
	v_add_f32_e32 v48, v48, v137
	s_or_b32 s0, s7, 3
	s_or_b32 s8, s0, s6
	s_ashr_i32 s9, s8, 31
	s_lshl_b64 s[8:9], s[8:9], 14
	v_lshl_add_u64 v[52:53], v[38:39], 0, s[8:9]
	s_cmp_gt_u32 s0, 62
	global_store_dword v[52:53], v48, off
	s_cbranch_scc1 .LBB0_94
	s_waitcnt vmcnt(6)
	ds_write_b128 v135, v[24:27] offset:20480
	s_waitcnt vmcnt(5)
	ds_write_b128 v136, v[28:31] offset:28672
	ds_write_b32 v51, v48 offset:2048
	s_cmp_gt_u32 s0, 58
	s_waitcnt vmcnt(4)
	v_mov_b32_e32 v48, v47
	s_cbranch_scc1 .LBB0_112
	s_lshl_b32 s0, s0, 13
	s_add_i32 s12, s0, 0x8000
	s_lshl_b64 s[0:1], s[12:13], 2
	s_add_u32 s8, s4, s0
	s_addc_u32 s9, s5, s1
	v_lshl_add_u64 v[24:25], v[34:35], 2, s[8:9]
	v_lshl_add_u64 v[28:29], v[36:37], 2, s[8:9]
	v_lshl_add_u64 v[52:53], v[32:33], 0, s[0:1]
	global_load_dwordx4 v[24:27], v[24:25], off
	s_nop 0
	global_load_dwordx4 v[28:31], v[28:29], off
	s_nop 0
	global_load_dword v48, v[52:53], off
; #define LAS __attribute__((address_space(3)))
; __device__ __forceinline__ void rw_combine8(const int tid, LAS float* lds, const float* PQ, float* SIN, int task) {
;     ...
;         for (int d = 0; d < 4; ++d) {
;             const int c = c0 + d;
;             SIN[(size_t)(head * NCH + c) * 4096 + (r0 + row) * 64 + k] = sval;
;             if (c < NCH - 1) {
;                 LAS float* Sl = Sl0 + (d & 1) * 512; LAS float* Pl = Pl0 + (d & 1) * 4096;
;                 *(LAS f32x4*)(Pl + tid * 4) = pp0[d]; *(LAS f32x4*)(Pl + (tid + NTHR) * 4) = pp1[d]; Sl[row * 64 + k] = sval;
;                 float acc = pq[d];
;                 if (c + 4 < NCH - 1) { pp0[d] = *(const f32x4*)(Pb + (size_t)(c + 4) * 8192 + tid * 4); pp1[d] = *(const f32x4*)(Pb + (size_t)(c + 4) * 8192 + (tid + NTHR) * 4); pq[d] = Qb[(size_t)(c + 4) * 8192]; }
;                 __syncthreads();
; #pragma unroll 1
;                 for (int j8 = 0; j8 < 2; ++j8) {
; #pragma unroll
;                     for (int jj = 0; jj < 8; ++jj) { const int j4 = j8 * 8 + jj; const f32x4 s4 = *(const LAS f32x4*)(Sl + row * 64 + j4 * 4);
;                         acc += s4.x * Pl[(j4 * 4) * 64 + k] + s4.y * Pl[(j4 * 4 + 1) * 64 + k] + s4.z * Pl[(j4 * 4 + 2) * 64 + k] + s4.w * Pl[(j4 * 4 + 3) * 64 + k]; } }
;                 sval = acc;
.LBB0_112:
	s_mov_b32 s8, 0
	s_mov_b64 s[0:1], -1
	s_waitcnt lgkmcnt(0)
	s_barrier
	ds_read_b128 v[52:55], v132 offset:2048
	ds_read_b128 v[56:59], v132 offset:2064
	ds_read_b128 v[60:63], v132 offset:2080
	ds_read_b128 v[64:67], v132 offset:2096
	ds_read_b128 v[68:71], v133 offset:20480
	ds_read_b128 v[72:75], v133 offset:20736
	ds_read_b128 v[76:79], v133 offset:20992
	ds_read_b128 v[80:83], v133 offset:21248
	ds_read_b128 v[84:87], v133 offset:21504
	ds_read_b128 v[88:91], v133 offset:21760
	ds_read_b128 v[92:95], v133 offset:22016
	ds_read_b128 v[96:99], v133 offset:22272
	ds_read_b128 v[100:103], v133 offset:22528
	ds_read_b128 v[104:107], v133 offset:22784
	ds_read_b128 v[108:111], v133 offset:23040
	ds_read_b128 v[112:115], v133 offset:23296
	ds_read_b128 v[116:119], v133 offset:23552
	ds_read_b128 v[120:123], v133 offset:23808
	ds_read_b128 v[124:127], v133 offset:24064
	ds_read_b128 v[128:131], v133 offset:24320
	s_waitcnt lgkmcnt(15)
	v_mul_f32_e32 v137, v52, v68
	v_mul_f32_e32 v138, v52, v69
	v_mul_f32_e32 v139, v52, v70
	v_mul_f32_e32 v140, v52, v71
	s_waitcnt lgkmcnt(14)
	v_fmac_f32_e32 v137, v53, v72
	v_fmac_f32_e32 v138, v53, v73
	v_fmac_f32_e32 v139, v53, v74
	v_fmac_f32_e32 v140, v53, v75
	s_waitcnt lgkmcnt(13)
	v_fmac_f32_e32 v137, v54, v76
	v_fmac_f32_e32 v138, v54, v77
	v_fmac_f32_e32 v139, v54, v78
	v_fmac_f32_e32 v140, v54, v79
	s_waitcnt lgkmcnt(12)
	v_fmac_f32_e32 v137, v55, v80
	v_fmac_f32_e32 v138, v55, v81
	v_fmac_f32_e32 v139, v55, v82
	v_fmac_f32_e32 v140, v55, v83
	s_waitcnt lgkmcnt(11)
	v_fmac_f32_e32 v137, v56, v84
	v_fmac_f32_e32 v138, v56, v85
	v_fmac_f32_e32 v139, v56, v86
	v_fmac_f32_e32 v140, v56, v87
	s_waitcnt lgkmcnt(10)
	v_fmac_f32_e32 v137, v57, v88
	v_fmac_f32_e32 v138, v57, v89
	v_fmac_f32_e32 v139, v57, v90
	v_fmac_f32_e32 v140, v57, v91
	s_waitcnt lgkmcnt(9)
	v_fmac_f32_e32 v137, v58, v92
	v_fmac_f32_e32 v138, v58, v93
	v_fmac_f32_e32 v139, v58, v94
	v_fmac_f32_e32 v140, v58, v95
	s_waitcnt lgkmcnt(8)
	v_fmac_f32_e32 v137, v59, v96
	v_fmac_f32_e32 v138, v59, v97
	v_fmac_f32_e32 v139, v59, v98
	v_fmac_f32_e32 v140, v59, v99
	s_waitcnt lgkmcnt(7)
	v_fmac_f32_e32 v137, v60, v100
	v_fmac_f32_e32 v138, v60, v101
	v_fmac_f32_e32 v139, v60, v102
	v_fmac_f32_e32 v140, v60, v103
	s_waitcnt lgkmcnt(6)
	v_fmac_f32_e32 v137, v61, v104
	v_fmac_f32_e32 v138, v61, v105
	v_fmac_f32_e32 v139, v61, v106
	v_fmac_f32_e32 v140, v61, v107
	s_waitcnt lgkmcnt(5)
	v_fmac_f32_e32 v137, v62, v108
	v_fmac_f32_e32 v138, v62, v109
	v_fmac_f32_e32 v139, v62, v110
	v_fmac_f32_e32 v140, v62, v111
	s_waitcnt lgkmcnt(4)
	v_fmac_f32_e32 v137, v63, v112
	v_fmac_f32_e32 v138, v63, v113
	v_fmac_f32_e32 v139, v63, v114
	v_fmac_f32_e32 v140, v63, v115
	s_waitcnt lgkmcnt(3)
	v_fmac_f32_e32 v137, v64, v116
	v_fmac_f32_e32 v138, v64, v117
	v_fmac_f32_e32 v139, v64, v118
	v_fmac_f32_e32 v140, v64, v119
	s_waitcnt lgkmcnt(2)
	v_fmac_f32_e32 v137, v65, v120
	v_fmac_f32_e32 v138, v65, v121
	v_fmac_f32_e32 v139, v65, v122
	v_fmac_f32_e32 v140, v65, v123
	s_waitcnt lgkmcnt(1)
	v_fmac_f32_e32 v137, v66, v124
	v_fmac_f32_e32 v138, v66, v125
	v_fmac_f32_e32 v139, v66, v126
	v_fmac_f32_e32 v140, v66, v127
	s_waitcnt lgkmcnt(0)
	v_fmac_f32_e32 v137, v67, v128
	v_fmac_f32_e32 v138, v67, v129
	v_fmac_f32_e32 v139, v67, v130
	v_fmac_f32_e32 v140, v67, v131
	v_cmp_eq_u32_e64 s[0:1], 1, v134
	v_add_f32_dpp v137, v137, v137 quad_perm:[1,0,3,2] row_mask:0xf bank_mask:0xf
	v_add_f32_dpp v138, v138, v138 quad_perm:[1,0,3,2] row_mask:0xf bank_mask:0xf
	v_add_f32_dpp v139, v139, v139 quad_perm:[1,0,3,2] row_mask:0xf bank_mask:0xf
	v_add_f32_dpp v140, v140, v140 quad_perm:[1,0,3,2] row_mask:0xf bank_mask:0xf
	v_cmp_eq_u32_e64 s[8:9], 2, v134
	v_add_f32_dpp v137, v137, v137 quad_perm:[2,3,0,1] row_mask:0xf bank_mask:0xf
	v_add_f32_dpp v138, v138, v138 quad_perm:[2,3,0,1] row_mask:0xf bank_mask:0xf
	v_add_f32_dpp v139, v139, v139 quad_perm:[2,3,0,1] row_mask:0xf bank_mask:0xf
	v_add_f32_dpp v140, v140, v140 quad_perm:[2,3,0,1] row_mask:0xf bank_mask:0xf
	v_cmp_eq_u32_e32 vcc, 3, v134
	s_nop 1
	v_cndmask_b32_e64 v137, v137, v138, s[0:1]
	v_cndmask_b32_e64 v137, v137, v139, s[8:9]
	v_cndmask_b32_e32 v137, v137, v140, vcc
	v_add_f32_e32 v47, v47, v137
	v_mov_b32_e32 v51, v47
	s_waitcnt vmcnt(0)
	v_mov_b32_e32 v47, v48
	s_branch .LBB0_95
